# weight conversions (prologue + P2b) remapped: each wave converts 16 columns x 32 k so loads are 64-byte row segments and stores are full 32-byte sectors of one output row
# speedup vs baseline: 1.0083x; 1.0083x over previous
.LBB0_20:
	v_writelane_b32 v253, s68, 40
	s_lshl_b32 s0, s80, 9
	v_add_u32_e32 v10, s0, v8
	v_writelane_b32 v253, s69, 41
	v_writelane_b32 v253, s70, 42
	v_writelane_b32 v253, s71, 43
	v_writelane_b32 v253, s72, 44
	v_writelane_b32 v253, s73, 45
	v_writelane_b32 v253, s74, 46
	v_writelane_b32 v253, s75, 47
	v_writelane_b32 v253, s0, 48
	s_lshl_b32 s92, s96, 9
	s_mov_b64 s[2:3], exec
	v_readlane_b32 s8, v253, 20
	v_readlane_b32 s9, v253, 21
	v_readlane_b32 s10, v253, 30
	v_readlane_b32 s11, v253, 31
	v_readlane_b32 s12, v253, 28
	v_readlane_b32 s13, v253, 29
	v_readlane_b32 s14, v253, 34
	v_readlane_b32 s15, v253, 35
	v_readlane_b32 s16, v253, 32
	v_readlane_b32 s17, v253, 33
	v_readlane_b32 s18, v253, 36
	v_readlane_b32 s19, v253, 37
	v_readlane_b32 s20, v253, 38
	v_readlane_b32 s21, v253, 39
	v_mov_b32_e32 v11, 0
	v_mov_b32_e32 v192, v10
	v_cmp_gt_u32_e32 vcc, 0x6d000, v192
	s_mov_b64 s[36:37], vcc
	v_lshrrev_b32_e32 v193, 6, v192
	s_mov_b32 s1, 0x12c9fb5
	v_mul_hi_u32 v194, v193, s1
	v_mul_u32_u24_e32 v193, 0xda, v194
	v_lshrrev_b32_e32 v232, 6, v192
	v_sub_u32_e32 v193, v232, v193
	v_bfe_u32 v232, v192, 4, 2
	v_lshl_add_u32 v232, v194, 2, v232
	v_and_b32_e32 v194, 15, v192
	v_lshl_add_u32 v194, v193, 4, v194
	v_mov_b32_e32 v193, v232
	v_mul_u32_u24_e32 v195, 0x37400, v193
	v_lshl_add_u32 v195, v194, 2, v195
	v_lshlrev_b32_e32 v196, 11, v194
	v_lshl_add_u32 v196, v193, 4, v196
	v_add_u32_e32 v196, 0x400000, v196
	s_mov_b64 exec, s[36:37]
	global_load_dword v104, v195, s[8:9]
	v_add_u32_e32 v195, 0x6e80, v195
	global_load_dword v105, v195, s[8:9]
	v_add_u32_e32 v195, 0x6e80, v195
	global_load_dword v106, v195, s[8:9]
	v_add_u32_e32 v195, 0x6e80, v195
	global_load_dword v107, v195, s[8:9]
	v_add_u32_e32 v195, 0x6e80, v195
	global_load_dword v108, v195, s[8:9]
	v_add_u32_e32 v195, 0x6e80, v195
	global_load_dword v109, v195, s[8:9]
	v_add_u32_e32 v195, 0x6e80, v195
	global_load_dword v110, v195, s[8:9]
	v_add_u32_e32 v195, 0x6e80, v195
	global_load_dword v111, v195, s[8:9]
	s_mov_b64 exec, s[2:3]
	s_mul_i32 s0, s92, 1
	v_add_u32_e32 v200, s0, v10
	v_cmp_gt_u32_e32 vcc, 0x6d000, v200
	s_mov_b64 s[38:39], vcc
	v_lshrrev_b32_e32 v201, 6, v200
	s_mov_b32 s1, 0x12c9fb5
	v_mul_hi_u32 v202, v201, s1
	v_mul_u32_u24_e32 v201, 0xda, v202
	v_lshrrev_b32_e32 v232, 6, v200
	v_sub_u32_e32 v201, v232, v201
	v_bfe_u32 v232, v200, 4, 2
	v_lshl_add_u32 v232, v202, 2, v232
	v_and_b32_e32 v202, 15, v200
	v_lshl_add_u32 v202, v201, 4, v202
	v_mov_b32_e32 v201, v232
	v_mul_u32_u24_e32 v203, 0x37400, v201
	v_lshl_add_u32 v203, v202, 2, v203
	v_lshlrev_b32_e32 v204, 11, v202
	v_lshl_add_u32 v204, v201, 4, v204
	v_add_u32_e32 v204, 0x400000, v204
	s_mov_b64 exec, s[38:39]
	global_load_dword v120, v203, s[8:9]
	v_add_u32_e32 v203, 0x6e80, v203
	global_load_dword v121, v203, s[8:9]
	v_add_u32_e32 v203, 0x6e80, v203
	global_load_dword v122, v203, s[8:9]
	v_add_u32_e32 v203, 0x6e80, v203
	global_load_dword v123, v203, s[8:9]
	v_add_u32_e32 v203, 0x6e80, v203
	global_load_dword v124, v203, s[8:9]
	v_add_u32_e32 v203, 0x6e80, v203
	global_load_dword v125, v203, s[8:9]
	v_add_u32_e32 v203, 0x6e80, v203
	global_load_dword v126, v203, s[8:9]
	v_add_u32_e32 v203, 0x6e80, v203
	global_load_dword v127, v203, s[8:9]
	s_mov_b64 exec, s[2:3]
	v_mov_b32_e32 v208, v10
	v_cmp_gt_u32_e32 vcc, 0x70000, v208
	s_mov_b64 s[40:41], vcc
	v_lshrrev_b32_e32 v209, 6, v208
	s_mov_b32 s1, 0x124924a
	v_mul_hi_u32 v210, v209, s1
	v_mul_u32_u24_e32 v209, 0xe0, v210
	v_lshrrev_b32_e32 v232, 6, v208
	v_sub_u32_e32 v209, v232, v209
	v_bfe_u32 v232, v208, 4, 2
	v_lshl_add_u32 v232, v210, 2, v232
	v_and_b32_e32 v210, 15, v208
	v_lshl_add_u32 v210, v209, 4, v210
	v_mov_b32_e32 v209, v232
	v_mul_u32_u24_e32 v211, 0x37400, v209
	v_lshl_add_u32 v211, v210, 2, v211
	v_add_u32_e32 v211, 0x3680, v211
	v_lshlrev_b32_e32 v212, 11, v210
	v_lshl_add_u32 v212, v209, 4, v212
	v_add_u32_e32 v212, 0xb00000, v212
	s_mov_b64 exec, s[40:41]
	global_load_dword v136, v211, s[8:9]
	v_add_u32_e32 v211, 0x6e80, v211
	global_load_dword v137, v211, s[8:9]
	v_add_u32_e32 v211, 0x6e80, v211
	global_load_dword v138, v211, s[8:9]
	v_add_u32_e32 v211, 0x6e80, v211
	global_load_dword v139, v211, s[8:9]
	v_add_u32_e32 v211, 0x6e80, v211
	global_load_dword v140, v211, s[8:9]
	v_add_u32_e32 v211, 0x6e80, v211
	global_load_dword v141, v211, s[8:9]
	v_add_u32_e32 v211, 0x6e80, v211
	global_load_dword v142, v211, s[8:9]
	v_add_u32_e32 v211, 0x6e80, v211
	global_load_dword v143, v211, s[8:9]
	s_mov_b64 exec, s[2:3]
	s_mul_i32 s0, s92, 1
	v_add_u32_e32 v216, s0, v10
	v_cmp_gt_u32_e32 vcc, 0x70000, v216
	s_mov_b64 s[42:43], vcc
	v_lshrrev_b32_e32 v217, 6, v216
	s_mov_b32 s1, 0x124924a
	v_mul_hi_u32 v218, v217, s1
	v_mul_u32_u24_e32 v217, 0xe0, v218
	v_lshrrev_b32_e32 v232, 6, v216
	v_sub_u32_e32 v217, v232, v217
	v_bfe_u32 v232, v216, 4, 2
	v_lshl_add_u32 v232, v218, 2, v232
	v_and_b32_e32 v218, 15, v216
	v_lshl_add_u32 v218, v217, 4, v218
	v_mov_b32_e32 v217, v232
	v_mul_u32_u24_e32 v219, 0x37400, v217
	v_lshl_add_u32 v219, v218, 2, v219
	v_add_u32_e32 v219, 0x3680, v219
	v_lshlrev_b32_e32 v220, 11, v218
	v_lshl_add_u32 v220, v217, 4, v220
	v_add_u32_e32 v220, 0xb00000, v220
	s_mov_b64 exec, s[42:43]
	global_load_dword v152, v219, s[8:9]
	v_add_u32_e32 v219, 0x6e80, v219
	global_load_dword v153, v219, s[8:9]
	v_add_u32_e32 v219, 0x6e80, v219
	global_load_dword v154, v219, s[8:9]
	v_add_u32_e32 v219, 0x6e80, v219
	global_load_dword v155, v219, s[8:9]
	v_add_u32_e32 v219, 0x6e80, v219
	global_load_dword v156, v219, s[8:9]
	v_add_u32_e32 v219, 0x6e80, v219
	global_load_dword v157, v219, s[8:9]
	v_add_u32_e32 v219, 0x6e80, v219
	global_load_dword v158, v219, s[8:9]
	v_add_u32_e32 v219, 0x6e80, v219
	global_load_dword v159, v219, s[8:9]
	s_mov_b64 exec, s[2:3]
	v_mov_b32_e32 v224, v10
	v_cmp_gt_u32_e32 vcc, 0x20000, v224
	s_mov_b64 s[44:45], vcc
	v_lshrrev_b32_e32 v225, 6, v224
	v_lshrrev_b32_e32 v226, 12, v224
	v_lshlrev_b32_e32 v225, 6, v226
	v_lshrrev_b32_e32 v232, 6, v224
	v_sub_u32_e32 v225, v232, v225
	v_bfe_u32 v232, v224, 4, 2
	v_lshl_add_u32 v232, v226, 2, v232
	v_and_b32_e32 v226, 15, v224
	v_lshl_add_u32 v226, v225, 4, v226
	v_mov_b32_e32 v225, v232
	v_mul_u32_u24_e32 v227, 0x8000, v225
	v_lshl_add_u32 v227, v226, 2, v227
	v_lshlrev_b32_e32 v228, 11, v226
	v_lshl_add_u32 v228, v225, 4, v228
	v_add_u32_e32 v228, 0x1700000, v228
	s_mov_b64 exec, s[44:45]
	global_load_dword v176, v227, s[70:71]
	v_add_u32_e32 v227, 0x1000, v227
	global_load_dword v177, v227, s[70:71]
	v_add_u32_e32 v227, 0x1000, v227
	global_load_dword v178, v227, s[70:71]
	v_add_u32_e32 v227, 0x1000, v227
	global_load_dword v179, v227, s[70:71]
	v_add_u32_e32 v227, 0x1000, v227
	global_load_dword v180, v227, s[70:71]
	v_add_u32_e32 v227, 0x1000, v227
	global_load_dword v181, v227, s[70:71]
	v_add_u32_e32 v227, 0x1000, v227
	global_load_dword v182, v227, s[70:71]
	v_add_u32_e32 v227, 0x1000, v227
	global_load_dword v183, v227, s[70:71]
	s_mov_b64 exec, s[2:3]
	s_waitcnt vmcnt(0)
	s_mov_b64 exec, s[36:37]
	v_cvt_pk_bf16_f32 v104, v104, v105
	v_cvt_pk_bf16_f32 v105, v106, v107
	v_cvt_pk_bf16_f32 v106, v108, v109
	v_cvt_pk_bf16_f32 v107, v110, v111
	global_store_dwordx4 v196, v[104:107], s[94:95]
	s_mov_b64 exec, s[2:3]
	s_mov_b64 exec, s[38:39]
	v_cvt_pk_bf16_f32 v120, v120, v121
	v_cvt_pk_bf16_f32 v121, v122, v123
	v_cvt_pk_bf16_f32 v122, v124, v125
	v_cvt_pk_bf16_f32 v123, v126, v127
	global_store_dwordx4 v204, v[120:123], s[94:95]
	s_mov_b64 exec, s[2:3]
	s_mov_b64 exec, s[40:41]
	v_cvt_pk_bf16_f32 v136, v136, v137
	v_cvt_pk_bf16_f32 v137, v138, v139
	v_cvt_pk_bf16_f32 v138, v140, v141
	v_cvt_pk_bf16_f32 v139, v142, v143
	global_store_dwordx4 v212, v[136:139], s[94:95]
	s_mov_b64 exec, s[2:3]
	s_mov_b64 exec, s[42:43]
	v_cvt_pk_bf16_f32 v152, v152, v153
	v_cvt_pk_bf16_f32 v153, v154, v155
	v_cvt_pk_bf16_f32 v154, v156, v157
	v_cvt_pk_bf16_f32 v155, v158, v159
	global_store_dwordx4 v220, v[152:155], s[94:95]
	s_mov_b64 exec, s[2:3]
	s_mov_b64 exec, s[44:45]
	v_cvt_pk_bf16_f32 v176, v176, v177
	v_cvt_pk_bf16_f32 v177, v178, v179
	v_cvt_pk_bf16_f32 v178, v180, v181
	v_cvt_pk_bf16_f32 v179, v182, v183
	global_store_dwordx4 v228, v[176:179], s[94:95]
	s_mov_b64 exec, s[2:3]
	s_mul_i32 s0, s92, 2
	v_add_u32_e32 v192, s0, v10
	v_cmp_gt_u32_e32 vcc, 0x6d000, v192
	s_mov_b64 s[36:37], vcc
	v_lshrrev_b32_e32 v193, 6, v192
	s_mov_b32 s1, 0x12c9fb5
	v_mul_hi_u32 v194, v193, s1
	v_mul_u32_u24_e32 v193, 0xda, v194
	v_lshrrev_b32_e32 v232, 6, v192
	v_sub_u32_e32 v193, v232, v193
	v_bfe_u32 v232, v192, 4, 2
	v_lshl_add_u32 v232, v194, 2, v232
	v_and_b32_e32 v194, 15, v192
	v_lshl_add_u32 v194, v193, 4, v194
	v_mov_b32_e32 v193, v232
	v_mul_u32_u24_e32 v195, 0x37400, v193
	v_lshl_add_u32 v195, v194, 2, v195
	v_lshlrev_b32_e32 v196, 11, v194
	v_lshl_add_u32 v196, v193, 4, v196
	v_add_u32_e32 v196, 0x400000, v196
	s_mov_b64 exec, s[36:37]
	global_load_dword v104, v195, s[8:9]
	v_add_u32_e32 v195, 0x6e80, v195
	global_load_dword v105, v195, s[8:9]
	v_add_u32_e32 v195, 0x6e80, v195
	global_load_dword v106, v195, s[8:9]
	v_add_u32_e32 v195, 0x6e80, v195
	global_load_dword v107, v195, s[8:9]
	v_add_u32_e32 v195, 0x6e80, v195
	global_load_dword v108, v195, s[8:9]
	v_add_u32_e32 v195, 0x6e80, v195
	global_load_dword v109, v195, s[8:9]
	v_add_u32_e32 v195, 0x6e80, v195
	global_load_dword v110, v195, s[8:9]
	v_add_u32_e32 v195, 0x6e80, v195
	global_load_dword v111, v195, s[8:9]
	s_mov_b64 exec, s[2:3]
	s_mul_i32 s0, s92, 3
	v_add_u32_e32 v200, s0, v10
	v_cmp_gt_u32_e32 vcc, 0x6d000, v200
	s_mov_b64 s[38:39], vcc
	v_lshrrev_b32_e32 v201, 6, v200
	s_mov_b32 s1, 0x12c9fb5
	v_mul_hi_u32 v202, v201, s1
	v_mul_u32_u24_e32 v201, 0xda, v202
	v_lshrrev_b32_e32 v232, 6, v200
	v_sub_u32_e32 v201, v232, v201
	v_bfe_u32 v232, v200, 4, 2
	v_lshl_add_u32 v232, v202, 2, v232
	v_and_b32_e32 v202, 15, v200
	v_lshl_add_u32 v202, v201, 4, v202
	v_mov_b32_e32 v201, v232
	v_mul_u32_u24_e32 v203, 0x37400, v201
	v_lshl_add_u32 v203, v202, 2, v203
	v_lshlrev_b32_e32 v204, 11, v202
	v_lshl_add_u32 v204, v201, 4, v204
	v_add_u32_e32 v204, 0x400000, v204
	s_mov_b64 exec, s[38:39]
	global_load_dword v120, v203, s[8:9]
	v_add_u32_e32 v203, 0x6e80, v203
	global_load_dword v121, v203, s[8:9]
	v_add_u32_e32 v203, 0x6e80, v203
	global_load_dword v122, v203, s[8:9]
	v_add_u32_e32 v203, 0x6e80, v203
	global_load_dword v123, v203, s[8:9]
	v_add_u32_e32 v203, 0x6e80, v203
	global_load_dword v124, v203, s[8:9]
	v_add_u32_e32 v203, 0x6e80, v203
	global_load_dword v125, v203, s[8:9]
	v_add_u32_e32 v203, 0x6e80, v203
	global_load_dword v126, v203, s[8:9]
	v_add_u32_e32 v203, 0x6e80, v203
	global_load_dword v127, v203, s[8:9]
	s_mov_b64 exec, s[2:3]
	s_mul_i32 s0, s92, 2
	v_add_u32_e32 v208, s0, v10
	v_cmp_gt_u32_e32 vcc, 0x70000, v208
	s_mov_b64 s[40:41], vcc
	v_lshrrev_b32_e32 v209, 6, v208
	s_mov_b32 s1, 0x124924a
	v_mul_hi_u32 v210, v209, s1
	v_mul_u32_u24_e32 v209, 0xe0, v210
	v_lshrrev_b32_e32 v232, 6, v208
	v_sub_u32_e32 v209, v232, v209
	v_bfe_u32 v232, v208, 4, 2
	v_lshl_add_u32 v232, v210, 2, v232
	v_and_b32_e32 v210, 15, v208
	v_lshl_add_u32 v210, v209, 4, v210
	v_mov_b32_e32 v209, v232
	v_mul_u32_u24_e32 v211, 0x37400, v209
	v_lshl_add_u32 v211, v210, 2, v211
	v_add_u32_e32 v211, 0x3680, v211
	v_lshlrev_b32_e32 v212, 11, v210
	v_lshl_add_u32 v212, v209, 4, v212
	v_add_u32_e32 v212, 0xb00000, v212
	s_mov_b64 exec, s[40:41]
	global_load_dword v136, v211, s[8:9]
	v_add_u32_e32 v211, 0x6e80, v211
	global_load_dword v137, v211, s[8:9]
	v_add_u32_e32 v211, 0x6e80, v211
	global_load_dword v138, v211, s[8:9]
	v_add_u32_e32 v211, 0x6e80, v211
	global_load_dword v139, v211, s[8:9]
	v_add_u32_e32 v211, 0x6e80, v211
	global_load_dword v140, v211, s[8:9]
	v_add_u32_e32 v211, 0x6e80, v211
	global_load_dword v141, v211, s[8:9]
	v_add_u32_e32 v211, 0x6e80, v211
	global_load_dword v142, v211, s[8:9]
	v_add_u32_e32 v211, 0x6e80, v211
	global_load_dword v143, v211, s[8:9]
	s_mov_b64 exec, s[2:3]
	s_mul_i32 s0, s92, 3
	v_add_u32_e32 v216, s0, v10
	v_cmp_gt_u32_e32 vcc, 0x70000, v216
	s_mov_b64 s[42:43], vcc
	v_lshrrev_b32_e32 v217, 6, v216
	s_mov_b32 s1, 0x124924a
	v_mul_hi_u32 v218, v217, s1
	v_mul_u32_u24_e32 v217, 0xe0, v218
	v_lshrrev_b32_e32 v232, 6, v216
	v_sub_u32_e32 v217, v232, v217
	v_bfe_u32 v232, v216, 4, 2
	v_lshl_add_u32 v232, v218, 2, v232
	v_and_b32_e32 v218, 15, v216
	v_lshl_add_u32 v218, v217, 4, v218
	v_mov_b32_e32 v217, v232
	v_mul_u32_u24_e32 v219, 0x37400, v217
	v_lshl_add_u32 v219, v218, 2, v219
	v_add_u32_e32 v219, 0x3680, v219
	v_lshlrev_b32_e32 v220, 11, v218
	v_lshl_add_u32 v220, v217, 4, v220
	v_add_u32_e32 v220, 0xb00000, v220
	s_mov_b64 exec, s[42:43]
	global_load_dword v152, v219, s[8:9]
	v_add_u32_e32 v219, 0x6e80, v219
	global_load_dword v153, v219, s[8:9]
	v_add_u32_e32 v219, 0x6e80, v219
	global_load_dword v154, v219, s[8:9]
	v_add_u32_e32 v219, 0x6e80, v219
	global_load_dword v155, v219, s[8:9]
	v_add_u32_e32 v219, 0x6e80, v219
	global_load_dword v156, v219, s[8:9]
	v_add_u32_e32 v219, 0x6e80, v219
	global_load_dword v157, v219, s[8:9]
	v_add_u32_e32 v219, 0x6e80, v219
	global_load_dword v158, v219, s[8:9]
	v_add_u32_e32 v219, 0x6e80, v219
	global_load_dword v159, v219, s[8:9]
	s_mov_b64 exec, s[2:3]
	v_mov_b32_e32 v224, v10
	v_cmp_gt_u32_e32 vcc, 0x8000, v224
	s_mov_b64 s[44:45], vcc
	v_lshrrev_b32_e32 v225, 6, v224
	v_lshrrev_b32_e32 v226, 11, v224
	v_lshlrev_b32_e32 v225, 5, v226
	v_lshrrev_b32_e32 v232, 6, v224
	v_sub_u32_e32 v225, v232, v225
	v_bfe_u32 v232, v224, 4, 2
	v_lshl_add_u32 v232, v226, 2, v232
	v_and_b32_e32 v226, 15, v224
	v_lshl_add_u32 v226, v225, 4, v226
	v_mov_b32_e32 v225, v232
	v_mul_u32_u24_e32 v227, 0x4000, v225
	v_lshl_add_u32 v227, v226, 2, v227
	v_lshlrev_b32_e32 v228, 10, v226
	v_lshl_add_u32 v228, v225, 4, v228
	v_add_u32_e32 v228, 0x1300000, v228
	s_mov_b64 exec, s[44:45]
	global_load_dword v176, v227, s[66:67]
	v_add_u32_e32 v227, 0x800, v227
	global_load_dword v177, v227, s[66:67]
	v_add_u32_e32 v227, 0x800, v227
	global_load_dword v178, v227, s[66:67]
	v_add_u32_e32 v227, 0x800, v227
	global_load_dword v179, v227, s[66:67]
	v_add_u32_e32 v227, 0x800, v227
	global_load_dword v180, v227, s[66:67]
	v_add_u32_e32 v227, 0x800, v227
	global_load_dword v181, v227, s[66:67]
	v_add_u32_e32 v227, 0x800, v227
	global_load_dword v182, v227, s[66:67]
	v_add_u32_e32 v227, 0x800, v227
	global_load_dword v183, v227, s[66:67]
	s_mov_b64 exec, s[2:3]
	s_waitcnt vmcnt(0)
	s_mov_b64 exec, s[36:37]
	v_cvt_pk_bf16_f32 v104, v104, v105
	v_cvt_pk_bf16_f32 v105, v106, v107
	v_cvt_pk_bf16_f32 v106, v108, v109
	v_cvt_pk_bf16_f32 v107, v110, v111
	global_store_dwordx4 v196, v[104:107], s[94:95]
	s_mov_b64 exec, s[2:3]
	s_mov_b64 exec, s[38:39]
	v_cvt_pk_bf16_f32 v120, v120, v121
	v_cvt_pk_bf16_f32 v121, v122, v123
	v_cvt_pk_bf16_f32 v122, v124, v125
	v_cvt_pk_bf16_f32 v123, v126, v127
	global_store_dwordx4 v204, v[120:123], s[94:95]
	s_mov_b64 exec, s[2:3]
	s_mov_b64 exec, s[40:41]
	v_cvt_pk_bf16_f32 v136, v136, v137
	v_cvt_pk_bf16_f32 v137, v138, v139
	v_cvt_pk_bf16_f32 v138, v140, v141
	v_cvt_pk_bf16_f32 v139, v142, v143
	global_store_dwordx4 v212, v[136:139], s[94:95]
	s_mov_b64 exec, s[2:3]
	s_mov_b64 exec, s[42:43]
	v_cvt_pk_bf16_f32 v152, v152, v153
	v_cvt_pk_bf16_f32 v153, v154, v155
	v_cvt_pk_bf16_f32 v154, v156, v157
	v_cvt_pk_bf16_f32 v155, v158, v159
	global_store_dwordx4 v220, v[152:155], s[94:95]
	s_mov_b64 exec, s[2:3]
	s_mov_b64 exec, s[44:45]
	v_cvt_pk_bf16_f32 v176, v176, v177
	v_cvt_pk_bf16_f32 v177, v178, v179
	v_cvt_pk_bf16_f32 v178, v180, v181
	v_cvt_pk_bf16_f32 v179, v182, v183
	global_store_dwordx4 v228, v[176:179], s[94:95]
	s_mov_b64 exec, s[2:3]
	v_mov_b32_e32 v192, v10
	v_cmp_gt_u32_e32 vcc, 0x6000, v192
	s_mov_b64 s[36:37], vcc
	v_lshrrev_b32_e32 v193, 6, v192
	s_mov_b32 s1, 0x5555556
	v_mul_hi_u32 v194, v193, s1
	v_mul_u32_u24_e32 v193, 0x30, v194
	v_lshrrev_b32_e32 v232, 6, v192
	v_sub_u32_e32 v193, v232, v193
	v_bfe_u32 v232, v192, 4, 2
	v_lshl_add_u32 v232, v194, 2, v232
	v_and_b32_e32 v194, 15, v192
	v_lshl_add_u32 v194, v193, 4, v194
	v_mov_b32_e32 v193, v232
	v_mul_u32_u24_e32 v195, 0x6000, v193
	v_lshl_add_u32 v195, v194, 2, v195
	v_lshlrev_b32_e32 v196, 9, v194
	v_lshl_add_u32 v196, v193, 4, v196
	v_add_u32_e32 v196, 0x1200000, v196
	v_lshlrev_b32_e32 v197, 5, v193
	s_mov_b64 exec, s[36:37]
	global_load_dword v104, v195, s[10:11]
	v_add_u32_e32 v195, 0xc00, v195
	global_load_dword v105, v195, s[10:11]
	v_add_u32_e32 v195, 0xc00, v195
	global_load_dword v106, v195, s[10:11]
	v_add_u32_e32 v195, 0xc00, v195
	global_load_dword v107, v195, s[10:11]
	v_add_u32_e32 v195, 0xc00, v195
	global_load_dword v108, v195, s[10:11]
	v_add_u32_e32 v195, 0xc00, v195
	global_load_dword v109, v195, s[10:11]
	v_add_u32_e32 v195, 0xc00, v195
	global_load_dword v110, v195, s[10:11]
	v_add_u32_e32 v195, 0xc00, v195
	global_load_dword v111, v195, s[10:11]
	global_load_dwordx4 v[112:115], v197, s[12:13]
	global_load_dwordx4 v[116:119], v197, s[12:13] offset:16
	s_mov_b64 exec, s[2:3]
	v_mov_b32_e32 v200, v10
	v_cmp_gt_u32_e32 vcc, 0x4000, v200
	s_mov_b64 s[38:39], vcc
	v_lshrrev_b32_e32 v201, 6, v200
	v_lshrrev_b32_e32 v202, 12, v200
	v_lshlrev_b32_e32 v201, 6, v202
	v_lshrrev_b32_e32 v232, 6, v200
	v_sub_u32_e32 v201, v232, v201
	v_bfe_u32 v232, v200, 4, 2
	v_lshl_add_u32 v232, v202, 2, v232
	v_and_b32_e32 v202, 15, v200
	v_lshl_add_u32 v202, v201, 4, v202
	v_mov_b32_e32 v201, v232
	v_mul_u32_u24_e32 v203, 0x8000, v201
	v_lshl_add_u32 v203, v202, 2, v203
	v_lshlrev_b32_e32 v204, 8, v202
	v_lshl_add_u32 v204, v201, 4, v204
	v_add_u32_e32 v204, 0x1280000, v204
	v_lshlrev_b32_e32 v205, 5, v201
	s_mov_b64 exec, s[38:39]
	global_load_dword v120, v203, s[14:15]
	v_add_u32_e32 v203, 0x1000, v203
	global_load_dword v121, v203, s[14:15]
	v_add_u32_e32 v203, 0x1000, v203
	global_load_dword v122, v203, s[14:15]
	v_add_u32_e32 v203, 0x1000, v203
	global_load_dword v123, v203, s[14:15]
	v_add_u32_e32 v203, 0x1000, v203
	global_load_dword v124, v203, s[14:15]
	v_add_u32_e32 v203, 0x1000, v203
	global_load_dword v125, v203, s[14:15]
	v_add_u32_e32 v203, 0x1000, v203
	global_load_dword v126, v203, s[14:15]
	v_add_u32_e32 v203, 0x1000, v203
	global_load_dword v127, v203, s[14:15]
	global_load_dwordx4 v[128:131], v205, s[16:17]
	global_load_dwordx4 v[132:135], v205, s[16:17] offset:16
	s_mov_b64 exec, s[2:3]
	v_mov_b32_e32 v208, v10
	v_cmp_gt_u32_e32 vcc, 0x10000, v208
	s_mov_b64 s[40:41], vcc
	v_lshrrev_b32_e32 v209, 6, v208
	v_lshrrev_b32_e32 v210, 12, v208
	v_lshlrev_b32_e32 v209, 6, v210
	v_lshrrev_b32_e32 v232, 6, v208
	v_sub_u32_e32 v209, v232, v209
	v_bfe_u32 v232, v208, 4, 2
	v_lshl_add_u32 v232, v210, 2, v232
	v_and_b32_e32 v210, 15, v208
	v_lshl_add_u32 v210, v209, 4, v210
	v_mov_b32_e32 v209, v232
	v_mul_u32_u24_e32 v211, 0x8000, v209
	v_lshl_add_u32 v211, v210, 2, v211
	v_lshlrev_b32_e32 v212, 10, v210
	v_lshl_add_u32 v212, v209, 4, v212
	v_add_u32_e32 v212, 0x1400000, v212
	s_mov_b64 exec, s[40:41]
	global_load_dword v136, v211, s[18:19]
	v_add_u32_e32 v211, 0x1000, v211
	global_load_dword v137, v211, s[18:19]
	v_add_u32_e32 v211, 0x1000, v211
	global_load_dword v138, v211, s[18:19]
	v_add_u32_e32 v211, 0x1000, v211
	global_load_dword v139, v211, s[18:19]
	v_add_u32_e32 v211, 0x1000, v211
	global_load_dword v140, v211, s[18:19]
	v_add_u32_e32 v211, 0x1000, v211
	global_load_dword v141, v211, s[18:19]
	v_add_u32_e32 v211, 0x1000, v211
	global_load_dword v142, v211, s[18:19]
	v_add_u32_e32 v211, 0x1000, v211
	global_load_dword v143, v211, s[18:19]
	s_mov_b64 exec, s[2:3]
	v_mov_b32_e32 v216, v10
	v_cmp_gt_u32_e32 vcc, 0x10000, v216
	s_mov_b64 s[42:43], vcc
	v_lshrrev_b32_e32 v217, 6, v216
	v_lshrrev_b32_e32 v218, 12, v216
	v_lshlrev_b32_e32 v217, 6, v218
	v_lshrrev_b32_e32 v232, 6, v216
	v_sub_u32_e32 v217, v232, v217
	v_bfe_u32 v232, v216, 4, 2
	v_lshl_add_u32 v232, v218, 2, v232
	v_and_b32_e32 v218, 15, v216
	v_lshl_add_u32 v218, v217, 4, v218
	v_mov_b32_e32 v217, v232
	v_mul_u32_u24_e32 v219, 0x8000, v217
	v_lshl_add_u32 v219, v218, 2, v219
	v_lshlrev_b32_e32 v220, 10, v218
	v_lshl_add_u32 v220, v217, 4, v220
	v_add_u32_e32 v220, 0x1500000, v220
	s_mov_b64 exec, s[42:43]
	global_load_dword v152, v219, s[20:21]
	v_add_u32_e32 v219, 0x1000, v219
	global_load_dword v153, v219, s[20:21]
	v_add_u32_e32 v219, 0x1000, v219
	global_load_dword v154, v219, s[20:21]
	v_add_u32_e32 v219, 0x1000, v219
	global_load_dword v155, v219, s[20:21]
	v_add_u32_e32 v219, 0x1000, v219
	global_load_dword v156, v219, s[20:21]
	v_add_u32_e32 v219, 0x1000, v219
	global_load_dword v157, v219, s[20:21]
	v_add_u32_e32 v219, 0x1000, v219
	global_load_dword v158, v219, s[20:21]
	v_add_u32_e32 v219, 0x1000, v219
	global_load_dword v159, v219, s[20:21]
	s_mov_b64 exec, s[2:3]
	v_mov_b32_e32 v224, v10
	v_cmp_gt_u32_e32 vcc, 0x10000, v224
	s_mov_b64 s[44:45], vcc
	v_lshrrev_b32_e32 v225, 6, v224
	v_lshrrev_b32_e32 v226, 12, v224
	v_lshlrev_b32_e32 v225, 6, v226
	v_lshrrev_b32_e32 v232, 6, v224
	v_sub_u32_e32 v225, v232, v225
	v_bfe_u32 v232, v224, 4, 2
	v_lshl_add_u32 v232, v226, 2, v232
	v_and_b32_e32 v226, 15, v224
	v_lshl_add_u32 v226, v225, 4, v226
	v_mov_b32_e32 v225, v232
	v_mul_u32_u24_e32 v227, 0x8000, v225
	v_lshl_add_u32 v227, v226, 2, v227
	v_lshlrev_b32_e32 v228, 10, v226
	v_lshl_add_u32 v228, v225, 4, v228
	v_add_u32_e32 v228, 0x1600000, v228
	s_mov_b64 exec, s[44:45]
	global_load_dword v176, v227, s[68:69]
	v_add_u32_e32 v227, 0x1000, v227
	global_load_dword v177, v227, s[68:69]
	v_add_u32_e32 v227, 0x1000, v227
	global_load_dword v178, v227, s[68:69]
	v_add_u32_e32 v227, 0x1000, v227
	global_load_dword v179, v227, s[68:69]
	v_add_u32_e32 v227, 0x1000, v227
	global_load_dword v180, v227, s[68:69]
	v_add_u32_e32 v227, 0x1000, v227
	global_load_dword v181, v227, s[68:69]
	v_add_u32_e32 v227, 0x1000, v227
	global_load_dword v182, v227, s[68:69]
	v_add_u32_e32 v227, 0x1000, v227
	global_load_dword v183, v227, s[68:69]
	s_mov_b64 exec, s[2:3]
	s_waitcnt vmcnt(0)
	s_mov_b64 exec, s[36:37]
	v_mul_f32_e32 v104, v104, v112
	v_mul_f32_e32 v105, v105, v113
	v_mul_f32_e32 v106, v106, v114
	v_mul_f32_e32 v107, v107, v115
	v_mul_f32_e32 v108, v108, v116
	v_mul_f32_e32 v109, v109, v117
	v_mul_f32_e32 v110, v110, v118
	v_mul_f32_e32 v111, v111, v119
	v_cvt_pk_bf16_f32 v104, v104, v105
	v_cvt_pk_bf16_f32 v105, v106, v107
	v_cvt_pk_bf16_f32 v106, v108, v109
	v_cvt_pk_bf16_f32 v107, v110, v111
	global_store_dwordx4 v196, v[104:107], s[94:95]
	s_mov_b64 exec, s[2:3]
	s_mov_b64 exec, s[38:39]
	v_mul_f32_e32 v120, v120, v128
	v_mul_f32_e32 v121, v121, v129
	v_mul_f32_e32 v122, v122, v130
	v_mul_f32_e32 v123, v123, v131
	v_mul_f32_e32 v124, v124, v132
	v_mul_f32_e32 v125, v125, v133
	v_mul_f32_e32 v126, v126, v134
	v_mul_f32_e32 v127, v127, v135
	v_cvt_pk_bf16_f32 v120, v120, v121
	v_cvt_pk_bf16_f32 v121, v122, v123
	v_cvt_pk_bf16_f32 v122, v124, v125
	v_cvt_pk_bf16_f32 v123, v126, v127
	global_store_dwordx4 v204, v[120:123], s[94:95]
	s_mov_b64 exec, s[2:3]
	s_mov_b64 exec, s[40:41]
	v_cvt_pk_bf16_f32 v136, v136, v137
	v_cvt_pk_bf16_f32 v137, v138, v139
	v_cvt_pk_bf16_f32 v138, v140, v141
	v_cvt_pk_bf16_f32 v139, v142, v143
	global_store_dwordx4 v212, v[136:139], s[94:95]
	s_mov_b64 exec, s[2:3]
	s_mov_b64 exec, s[42:43]
	v_cvt_pk_bf16_f32 v152, v152, v153
	v_cvt_pk_bf16_f32 v153, v154, v155
	v_cvt_pk_bf16_f32 v154, v156, v157
	v_cvt_pk_bf16_f32 v155, v158, v159
	global_store_dwordx4 v220, v[152:155], s[94:95]
	s_mov_b64 exec, s[2:3]
	s_mov_b64 exec, s[44:45]
	v_cvt_pk_bf16_f32 v176, v176, v177
	v_cvt_pk_bf16_f32 v177, v178, v179
	v_cvt_pk_bf16_f32 v178, v180, v181
	v_cvt_pk_bf16_f32 v179, v182, v183
	global_store_dwordx4 v228, v[176:179], s[94:95]
	s_mov_b64 exec, s[2:3]
	v_cmp_gt_u32_e32 vcc, 0x3000, v10
	v_lshlrev_b32_e32 v192, 4, v10
	v_add_u32_e32 v192, 0xad0000, v192
	v_mov_b32_e32 v104, 0
	v_mov_b32_e32 v105, 0
	v_mov_b32_e32 v106, 0
	v_mov_b32_e32 v107, 0
	s_and_b64 exec, s[2:3], vcc
	global_store_dwordx4 v192, v[104:107], s[94:95]
	s_mov_b64 exec, s[2:3]
	.p2align 6
	s_nop 0
	s_nop 0

.LBB0_373:
	s_or_b64 exec, exec, s[30:31]
	v_readlane_b32 s0, v253, 0
	v_readlane_b32 s1, v253, 1
	s_add_i32 s0, s45, 1
	v_writelane_b32 v255, s0, 29
	s_cmp_lg_u32 s45, 3
	s_cselect_b64 s[4:5], -1, 0
	v_writelane_b32 v255, s1, 30
	v_readlane_b32 s0, v254, 11
	v_readlane_b32 s1, v254, 12
	v_writelane_b32 v255, s4, 31
	s_and_b64 s[0:1], s[0:1], s[4:5]
	v_mov_b32_e32 v26, v170
	v_readlane_b32 s2, v253, 2
	v_readlane_b32 s3, v253, 3
	v_writelane_b32 v255, s5, 32
	s_and_b64 vcc, exec, s[0:1]
	s_waitcnt lgkmcnt(0)
	s_barrier
	s_cbranch_vccz .LBB0_438
	s_mov_b64 s[20:21], exec
	v_readlane_b32 s0, v254, 13
	v_readlane_b32 s23, v255, 29
	v_readlane_b32 s4, v253, 20
	v_readlane_b32 s5, v253, 21
	v_readlane_b32 s6, v253, 30
	v_readlane_b32 s7, v253, 31
	v_readlane_b32 s8, v253, 28
	v_readlane_b32 s9, v253, 29
	s_nop 1
	v_add_u32_e32 v27, s0, v26
	s_mul_hi_u32 s1, s23, 0x1ba0000
	s_mul_i32 s0, s23, 0x1ba0000
	s_add_u32 s4, s4, s0
	s_addc_u32 s5, s5, s1
	s_mul_i32 s0, s23, 0xc0000
	s_add_u32 s6, s6, s0
	s_addc_u32 s7, s7, 0
	s_lshl_b32 s0, s23, 10
	s_add_u32 s8, s8, s0
	s_addc_u32 s9, s9, 0
	v_mov_b32_e32 v38, v27
	v_cmp_gt_u32_e32 vcc, 0x6d000, v38
	s_mov_b64 s[10:11], vcc
	v_lshrrev_b32_e32 v39, 6, v38
	s_mov_b32 s22, 0x12c9fb5
	v_mul_hi_u32 v40, v39, s22
	v_mul_u32_u24_e32 v39, 0xda, v40
	v_lshrrev_b32_e32 v42, 6, v38
	v_sub_u32_e32 v39, v42, v39
	v_bfe_u32 v42, v38, 4, 2
	v_lshl_add_u32 v42, v40, 2, v42
	v_and_b32_e32 v40, 15, v38
	v_lshl_add_u32 v40, v39, 4, v40
	v_mov_b32_e32 v39, v42
	v_mul_u32_u24_e32 v41, 0x37400, v39
	v_lshl_add_u32 v41, v40, 2, v41
	v_lshlrev_b32_e32 v24, 11, v40
	v_lshl_add_u32 v24, v39, 4, v24
	v_add_u32_e32 v24, 0x400000, v24
	s_mov_b64 exec, s[10:11]
	global_load_dword v0, v41, s[4:5]
	v_add_u32_e32 v41, 0x6e80, v41
	global_load_dword v1, v41, s[4:5]
	v_add_u32_e32 v41, 0x6e80, v41
	global_load_dword v2, v41, s[4:5]
	v_add_u32_e32 v41, 0x6e80, v41
	global_load_dword v3, v41, s[4:5]
	v_add_u32_e32 v41, 0x6e80, v41
	global_load_dword v4, v41, s[4:5]
	v_add_u32_e32 v41, 0x6e80, v41
	global_load_dword v5, v41, s[4:5]
	v_add_u32_e32 v41, 0x6e80, v41
	global_load_dword v6, v41, s[4:5]
	v_add_u32_e32 v41, 0x6e80, v41
	global_load_dword v7, v41, s[4:5]
	s_mov_b64 exec, s[20:21]
	s_mul_i32 s0, s76, 1
	v_add_u32_e32 v38, s0, v27
	v_cmp_gt_u32_e32 vcc, 0x6d000, v38
	s_mov_b64 s[12:13], vcc
	v_lshrrev_b32_e32 v39, 6, v38
	s_mov_b32 s22, 0x12c9fb5
	v_mul_hi_u32 v40, v39, s22
	v_mul_u32_u24_e32 v39, 0xda, v40
	v_lshrrev_b32_e32 v42, 6, v38
	v_sub_u32_e32 v39, v42, v39
	v_bfe_u32 v42, v38, 4, 2
	v_lshl_add_u32 v42, v40, 2, v42
	v_and_b32_e32 v40, 15, v38
	v_lshl_add_u32 v40, v39, 4, v40
	v_mov_b32_e32 v39, v42
	v_mul_u32_u24_e32 v41, 0x37400, v39
	v_lshl_add_u32 v41, v40, 2, v41
	v_lshlrev_b32_e32 v25, 11, v40
	v_lshl_add_u32 v25, v39, 4, v25
	v_add_u32_e32 v25, 0x400000, v25
	s_mov_b64 exec, s[12:13]
	global_load_dword v8, v41, s[4:5]
	v_add_u32_e32 v41, 0x6e80, v41
	global_load_dword v9, v41, s[4:5]
	v_add_u32_e32 v41, 0x6e80, v41
	global_load_dword v10, v41, s[4:5]
	v_add_u32_e32 v41, 0x6e80, v41
	global_load_dword v11, v41, s[4:5]
	v_add_u32_e32 v41, 0x6e80, v41
	global_load_dword v12, v41, s[4:5]
	v_add_u32_e32 v41, 0x6e80, v41
	global_load_dword v13, v41, s[4:5]
	v_add_u32_e32 v41, 0x6e80, v41
	global_load_dword v14, v41, s[4:5]
	v_add_u32_e32 v41, 0x6e80, v41
	global_load_dword v15, v41, s[4:5]
	s_mov_b64 exec, s[20:21]
	v_mov_b32_e32 v38, v27
	v_cmp_gt_u32_e32 vcc, 0x70000, v38
	s_mov_b64 s[14:15], vcc
	v_lshrrev_b32_e32 v39, 6, v38
	s_mov_b32 s22, 0x124924a
	v_mul_hi_u32 v40, v39, s22
	v_mul_u32_u24_e32 v39, 0xe0, v40
	v_lshrrev_b32_e32 v42, 6, v38
	v_sub_u32_e32 v39, v42, v39
	v_bfe_u32 v42, v38, 4, 2
	v_lshl_add_u32 v42, v40, 2, v42
	v_and_b32_e32 v40, 15, v38
	v_lshl_add_u32 v40, v39, 4, v40
	v_mov_b32_e32 v39, v42
	v_mul_u32_u24_e32 v41, 0x37400, v39
	v_lshl_add_u32 v41, v40, 2, v41
	v_add_u32_e32 v41, 0x3680, v41
	v_lshlrev_b32_e32 v36, 11, v40
	v_lshl_add_u32 v36, v39, 4, v36
	v_add_u32_e32 v36, 0xb00000, v36
	s_mov_b64 exec, s[14:15]
	global_load_dword v16, v41, s[4:5]
	v_add_u32_e32 v41, 0x6e80, v41
	global_load_dword v17, v41, s[4:5]
	v_add_u32_e32 v41, 0x6e80, v41
	global_load_dword v18, v41, s[4:5]
	v_add_u32_e32 v41, 0x6e80, v41
	global_load_dword v19, v41, s[4:5]
	v_add_u32_e32 v41, 0x6e80, v41
	global_load_dword v20, v41, s[4:5]
	v_add_u32_e32 v41, 0x6e80, v41
	global_load_dword v21, v41, s[4:5]
	v_add_u32_e32 v41, 0x6e80, v41
	global_load_dword v22, v41, s[4:5]
	v_add_u32_e32 v41, 0x6e80, v41
	global_load_dword v23, v41, s[4:5]
	s_mov_b64 exec, s[20:21]
	s_mul_i32 s0, s76, 1
	v_add_u32_e32 v38, s0, v27
	v_cmp_gt_u32_e32 vcc, 0x70000, v38
	s_mov_b64 s[16:17], vcc
	v_lshrrev_b32_e32 v39, 6, v38
	s_mov_b32 s22, 0x124924a
	v_mul_hi_u32 v40, v39, s22
	v_mul_u32_u24_e32 v39, 0xe0, v40
	v_lshrrev_b32_e32 v42, 6, v38
	v_sub_u32_e32 v39, v42, v39
	v_bfe_u32 v42, v38, 4, 2
	v_lshl_add_u32 v42, v40, 2, v42
	v_and_b32_e32 v40, 15, v38
	v_lshl_add_u32 v40, v39, 4, v40
	v_mov_b32_e32 v39, v42
	v_mul_u32_u24_e32 v41, 0x37400, v39
	v_lshl_add_u32 v41, v40, 2, v41
	v_add_u32_e32 v41, 0x3680, v41
	v_lshlrev_b32_e32 v37, 11, v40
	v_lshl_add_u32 v37, v39, 4, v37
	v_add_u32_e32 v37, 0xb00000, v37
	s_mov_b64 exec, s[16:17]
	global_load_dword v28, v41, s[4:5]
	v_add_u32_e32 v41, 0x6e80, v41
	global_load_dword v29, v41, s[4:5]
	v_add_u32_e32 v41, 0x6e80, v41
	global_load_dword v30, v41, s[4:5]
	v_add_u32_e32 v41, 0x6e80, v41
	global_load_dword v31, v41, s[4:5]
	v_add_u32_e32 v41, 0x6e80, v41
	global_load_dword v32, v41, s[4:5]
	v_add_u32_e32 v41, 0x6e80, v41
	global_load_dword v33, v41, s[4:5]
	v_add_u32_e32 v41, 0x6e80, v41
	global_load_dword v34, v41, s[4:5]
	v_add_u32_e32 v41, 0x6e80, v41
	global_load_dword v35, v41, s[4:5]
	s_mov_b64 exec, s[20:21]
	s_waitcnt vmcnt(0)
	s_mov_b64 exec, s[10:11]
	v_cvt_pk_bf16_f32 v0, v0, v1
	v_cvt_pk_bf16_f32 v1, v2, v3
	v_cvt_pk_bf16_f32 v2, v4, v5
	v_cvt_pk_bf16_f32 v3, v6, v7
	global_store_dwordx4 v24, v[0:3], s[2:3]
	s_mov_b64 exec, s[20:21]
	s_mov_b64 exec, s[12:13]
	v_cvt_pk_bf16_f32 v8, v8, v9
	v_cvt_pk_bf16_f32 v9, v10, v11
	v_cvt_pk_bf16_f32 v10, v12, v13
	v_cvt_pk_bf16_f32 v11, v14, v15
	global_store_dwordx4 v25, v[8:11], s[2:3]
	s_mov_b64 exec, s[20:21]
	s_mov_b64 exec, s[14:15]
	v_cvt_pk_bf16_f32 v16, v16, v17
	v_cvt_pk_bf16_f32 v17, v18, v19
	v_cvt_pk_bf16_f32 v18, v20, v21
	v_cvt_pk_bf16_f32 v19, v22, v23
	global_store_dwordx4 v36, v[16:19], s[2:3]
	s_mov_b64 exec, s[20:21]
	s_mov_b64 exec, s[16:17]
	v_cvt_pk_bf16_f32 v28, v28, v29
	v_cvt_pk_bf16_f32 v29, v30, v31
	v_cvt_pk_bf16_f32 v30, v32, v33
	v_cvt_pk_bf16_f32 v31, v34, v35
	global_store_dwordx4 v37, v[28:31], s[2:3]
	s_mov_b64 exec, s[20:21]
	s_mul_i32 s0, s76, 2
	v_add_u32_e32 v38, s0, v27
	v_cmp_gt_u32_e32 vcc, 0x6d000, v38
	s_mov_b64 s[10:11], vcc
	v_lshrrev_b32_e32 v39, 6, v38
	s_mov_b32 s22, 0x12c9fb5
	v_mul_hi_u32 v40, v39, s22
	v_mul_u32_u24_e32 v39, 0xda, v40
	v_lshrrev_b32_e32 v42, 6, v38
	v_sub_u32_e32 v39, v42, v39
	v_bfe_u32 v42, v38, 4, 2
	v_lshl_add_u32 v42, v40, 2, v42
	v_and_b32_e32 v40, 15, v38
	v_lshl_add_u32 v40, v39, 4, v40
	v_mov_b32_e32 v39, v42
	v_mul_u32_u24_e32 v41, 0x37400, v39
	v_lshl_add_u32 v41, v40, 2, v41
	v_lshlrev_b32_e32 v24, 11, v40
	v_lshl_add_u32 v24, v39, 4, v24
	v_add_u32_e32 v24, 0x400000, v24
	s_mov_b64 exec, s[10:11]
	global_load_dword v0, v41, s[4:5]
	v_add_u32_e32 v41, 0x6e80, v41
	global_load_dword v1, v41, s[4:5]
	v_add_u32_e32 v41, 0x6e80, v41
	global_load_dword v2, v41, s[4:5]
	v_add_u32_e32 v41, 0x6e80, v41
	global_load_dword v3, v41, s[4:5]
	v_add_u32_e32 v41, 0x6e80, v41
	global_load_dword v4, v41, s[4:5]
	v_add_u32_e32 v41, 0x6e80, v41
	global_load_dword v5, v41, s[4:5]
	v_add_u32_e32 v41, 0x6e80, v41
	global_load_dword v6, v41, s[4:5]
	v_add_u32_e32 v41, 0x6e80, v41
	global_load_dword v7, v41, s[4:5]
	s_mov_b64 exec, s[20:21]
	s_mul_i32 s0, s76, 3
	v_add_u32_e32 v38, s0, v27
	v_cmp_gt_u32_e32 vcc, 0x6d000, v38
	s_mov_b64 s[12:13], vcc
	v_lshrrev_b32_e32 v39, 6, v38
	s_mov_b32 s22, 0x12c9fb5
	v_mul_hi_u32 v40, v39, s22
	v_mul_u32_u24_e32 v39, 0xda, v40
	v_lshrrev_b32_e32 v42, 6, v38
	v_sub_u32_e32 v39, v42, v39
	v_bfe_u32 v42, v38, 4, 2
	v_lshl_add_u32 v42, v40, 2, v42
	v_and_b32_e32 v40, 15, v38
	v_lshl_add_u32 v40, v39, 4, v40
	v_mov_b32_e32 v39, v42
	v_mul_u32_u24_e32 v41, 0x37400, v39
	v_lshl_add_u32 v41, v40, 2, v41
	v_lshlrev_b32_e32 v25, 11, v40
	v_lshl_add_u32 v25, v39, 4, v25
	v_add_u32_e32 v25, 0x400000, v25
	s_mov_b64 exec, s[12:13]
	global_load_dword v8, v41, s[4:5]
	v_add_u32_e32 v41, 0x6e80, v41
	global_load_dword v9, v41, s[4:5]
	v_add_u32_e32 v41, 0x6e80, v41
	global_load_dword v10, v41, s[4:5]
	v_add_u32_e32 v41, 0x6e80, v41
	global_load_dword v11, v41, s[4:5]
	v_add_u32_e32 v41, 0x6e80, v41
	global_load_dword v12, v41, s[4:5]
	v_add_u32_e32 v41, 0x6e80, v41
	global_load_dword v13, v41, s[4:5]
	v_add_u32_e32 v41, 0x6e80, v41
	global_load_dword v14, v41, s[4:5]
	v_add_u32_e32 v41, 0x6e80, v41
	global_load_dword v15, v41, s[4:5]
	s_mov_b64 exec, s[20:21]
	s_mul_i32 s0, s76, 2
	v_add_u32_e32 v38, s0, v27
	v_cmp_gt_u32_e32 vcc, 0x70000, v38
	s_mov_b64 s[14:15], vcc
	v_lshrrev_b32_e32 v39, 6, v38
	s_mov_b32 s22, 0x124924a
	v_mul_hi_u32 v40, v39, s22
	v_mul_u32_u24_e32 v39, 0xe0, v40
	v_lshrrev_b32_e32 v42, 6, v38
	v_sub_u32_e32 v39, v42, v39
	v_bfe_u32 v42, v38, 4, 2
	v_lshl_add_u32 v42, v40, 2, v42
	v_and_b32_e32 v40, 15, v38
	v_lshl_add_u32 v40, v39, 4, v40
	v_mov_b32_e32 v39, v42
	v_mul_u32_u24_e32 v41, 0x37400, v39
	v_lshl_add_u32 v41, v40, 2, v41
	v_add_u32_e32 v41, 0x3680, v41
	v_lshlrev_b32_e32 v36, 11, v40
	v_lshl_add_u32 v36, v39, 4, v36
	v_add_u32_e32 v36, 0xb00000, v36
	s_mov_b64 exec, s[14:15]
	global_load_dword v16, v41, s[4:5]
	v_add_u32_e32 v41, 0x6e80, v41
	global_load_dword v17, v41, s[4:5]
	v_add_u32_e32 v41, 0x6e80, v41
	global_load_dword v18, v41, s[4:5]
	v_add_u32_e32 v41, 0x6e80, v41
	global_load_dword v19, v41, s[4:5]
	v_add_u32_e32 v41, 0x6e80, v41
	global_load_dword v20, v41, s[4:5]
	v_add_u32_e32 v41, 0x6e80, v41
	global_load_dword v21, v41, s[4:5]
	v_add_u32_e32 v41, 0x6e80, v41
	global_load_dword v22, v41, s[4:5]
	v_add_u32_e32 v41, 0x6e80, v41
	global_load_dword v23, v41, s[4:5]
	s_mov_b64 exec, s[20:21]
	s_mul_i32 s0, s76, 3
	v_add_u32_e32 v38, s0, v27
	v_cmp_gt_u32_e32 vcc, 0x70000, v38
	s_mov_b64 s[16:17], vcc
	v_lshrrev_b32_e32 v39, 6, v38
	s_mov_b32 s22, 0x124924a
	v_mul_hi_u32 v40, v39, s22
	v_mul_u32_u24_e32 v39, 0xe0, v40
	v_lshrrev_b32_e32 v42, 6, v38
	v_sub_u32_e32 v39, v42, v39
	v_bfe_u32 v42, v38, 4, 2
	v_lshl_add_u32 v42, v40, 2, v42
	v_and_b32_e32 v40, 15, v38
	v_lshl_add_u32 v40, v39, 4, v40
	v_mov_b32_e32 v39, v42
	v_mul_u32_u24_e32 v41, 0x37400, v39
	v_lshl_add_u32 v41, v40, 2, v41
	v_add_u32_e32 v41, 0x3680, v41
	v_lshlrev_b32_e32 v37, 11, v40
	v_lshl_add_u32 v37, v39, 4, v37
	v_add_u32_e32 v37, 0xb00000, v37
	s_mov_b64 exec, s[16:17]
	global_load_dword v28, v41, s[4:5]
	v_add_u32_e32 v41, 0x6e80, v41
	global_load_dword v29, v41, s[4:5]
	v_add_u32_e32 v41, 0x6e80, v41
	global_load_dword v30, v41, s[4:5]
	v_add_u32_e32 v41, 0x6e80, v41
	global_load_dword v31, v41, s[4:5]
	v_add_u32_e32 v41, 0x6e80, v41
	global_load_dword v32, v41, s[4:5]
	v_add_u32_e32 v41, 0x6e80, v41
	global_load_dword v33, v41, s[4:5]
	v_add_u32_e32 v41, 0x6e80, v41
	global_load_dword v34, v41, s[4:5]
	v_add_u32_e32 v41, 0x6e80, v41
	global_load_dword v35, v41, s[4:5]
	s_mov_b64 exec, s[20:21]
	s_waitcnt vmcnt(0)
	s_mov_b64 exec, s[10:11]
	v_cvt_pk_bf16_f32 v0, v0, v1
	v_cvt_pk_bf16_f32 v1, v2, v3
	v_cvt_pk_bf16_f32 v2, v4, v5
	v_cvt_pk_bf16_f32 v3, v6, v7
	global_store_dwordx4 v24, v[0:3], s[2:3]
	s_mov_b64 exec, s[20:21]
	s_mov_b64 exec, s[12:13]
	v_cvt_pk_bf16_f32 v8, v8, v9
	v_cvt_pk_bf16_f32 v9, v10, v11
	v_cvt_pk_bf16_f32 v10, v12, v13
	v_cvt_pk_bf16_f32 v11, v14, v15
	global_store_dwordx4 v25, v[8:11], s[2:3]
	s_mov_b64 exec, s[20:21]
	s_mov_b64 exec, s[14:15]
	v_cvt_pk_bf16_f32 v16, v16, v17
	v_cvt_pk_bf16_f32 v17, v18, v19
	v_cvt_pk_bf16_f32 v18, v20, v21
	v_cvt_pk_bf16_f32 v19, v22, v23
	global_store_dwordx4 v36, v[16:19], s[2:3]
	s_mov_b64 exec, s[20:21]
	s_mov_b64 exec, s[16:17]
	v_cvt_pk_bf16_f32 v28, v28, v29
	v_cvt_pk_bf16_f32 v29, v30, v31
	v_cvt_pk_bf16_f32 v30, v32, v33
	v_cvt_pk_bf16_f32 v31, v34, v35
	global_store_dwordx4 v37, v[28:31], s[2:3]
	s_mov_b64 exec, s[20:21]
	v_readlane_b32 s4, v253, 34
	v_readlane_b32 s5, v253, 35
	v_readlane_b32 s14, v253, 32
	v_readlane_b32 s15, v253, 33
	s_nop 1
	s_mul_i32 s0, s23, 0x80000
	s_add_u32 s4, s4, s0
	s_addc_u32 s5, s5, 0
	s_lshl_b32 s0, s23, 9
	s_add_u32 s14, s14, s0
	s_addc_u32 s15, s15, 0
	v_mov_b32_e32 v38, v27
	v_cmp_gt_u32_e32 vcc, 0x6000, v38
	s_mov_b64 s[10:11], vcc
	v_lshrrev_b32_e32 v39, 6, v38
	s_mov_b32 s22, 0x5555556
	v_mul_hi_u32 v40, v39, s22
	v_mul_u32_u24_e32 v39, 0x30, v40
	v_lshrrev_b32_e32 v42, 6, v38
	v_sub_u32_e32 v39, v42, v39
	v_bfe_u32 v42, v38, 4, 2
	v_lshl_add_u32 v42, v40, 2, v42
	v_and_b32_e32 v40, 15, v38
	v_lshl_add_u32 v40, v39, 4, v40
	v_mov_b32_e32 v39, v42
	v_mul_u32_u24_e32 v41, 0x6000, v39
	v_lshl_add_u32 v41, v40, 2, v41
	v_lshlrev_b32_e32 v24, 9, v40
	v_lshl_add_u32 v24, v39, 4, v24
	v_add_u32_e32 v24, 0x1200000, v24
	v_lshlrev_b32_e32 v42, 5, v39
	s_mov_b64 exec, s[10:11]
	global_load_dword v0, v41, s[6:7]
	v_add_u32_e32 v41, 0xc00, v41
	global_load_dword v1, v41, s[6:7]
	v_add_u32_e32 v41, 0xc00, v41
	global_load_dword v2, v41, s[6:7]
	v_add_u32_e32 v41, 0xc00, v41
	global_load_dword v3, v41, s[6:7]
	v_add_u32_e32 v41, 0xc00, v41
	global_load_dword v4, v41, s[6:7]
	v_add_u32_e32 v41, 0xc00, v41
	global_load_dword v5, v41, s[6:7]
	v_add_u32_e32 v41, 0xc00, v41
	global_load_dword v6, v41, s[6:7]
	v_add_u32_e32 v41, 0xc00, v41
	global_load_dword v7, v41, s[6:7]
	global_load_dwordx4 v[8:11], v42, s[8:9]
	global_load_dwordx4 v[12:15], v42, s[8:9] offset:16
	s_mov_b64 exec, s[20:21]
	v_mov_b32_e32 v38, v27
	v_cmp_gt_u32_e32 vcc, 0x4000, v38
	s_mov_b64 s[12:13], vcc
	v_lshrrev_b32_e32 v39, 6, v38
	v_lshrrev_b32_e32 v40, 12, v38
	v_lshlrev_b32_e32 v39, 6, v40
	v_lshrrev_b32_e32 v42, 6, v38
	v_sub_u32_e32 v39, v42, v39
	v_bfe_u32 v42, v38, 4, 2
	v_lshl_add_u32 v42, v40, 2, v42
	v_and_b32_e32 v40, 15, v38
	v_lshl_add_u32 v40, v39, 4, v40
	v_mov_b32_e32 v39, v42
	v_mul_u32_u24_e32 v41, 0x8000, v39
	v_lshl_add_u32 v41, v40, 2, v41
	v_lshlrev_b32_e32 v25, 8, v40
	v_lshl_add_u32 v25, v39, 4, v25
	v_add_u32_e32 v25, 0x1280000, v25
	v_lshlrev_b32_e32 v42, 5, v39
	s_mov_b64 exec, s[12:13]
	global_load_dword v16, v41, s[4:5]
	v_add_u32_e32 v41, 0x1000, v41
	global_load_dword v17, v41, s[4:5]
	v_add_u32_e32 v41, 0x1000, v41
	global_load_dword v18, v41, s[4:5]
	v_add_u32_e32 v41, 0x1000, v41
	global_load_dword v19, v41, s[4:5]
	v_add_u32_e32 v41, 0x1000, v41
	global_load_dword v20, v41, s[4:5]
	v_add_u32_e32 v41, 0x1000, v41
	global_load_dword v21, v41, s[4:5]
	v_add_u32_e32 v41, 0x1000, v41
	global_load_dword v22, v41, s[4:5]
	v_add_u32_e32 v41, 0x1000, v41
	global_load_dword v23, v41, s[4:5]
	global_load_dwordx4 v[28:31], v42, s[14:15]
	global_load_dwordx4 v[32:35], v42, s[14:15] offset:16
	s_mov_b64 exec, s[20:21]
	s_waitcnt vmcnt(0)
	s_mov_b64 exec, s[10:11]
	v_mul_f32_e32 v0, v0, v8
	v_mul_f32_e32 v1, v1, v9
	v_mul_f32_e32 v2, v2, v10
	v_mul_f32_e32 v3, v3, v11
	v_mul_f32_e32 v4, v4, v12
	v_mul_f32_e32 v5, v5, v13
	v_mul_f32_e32 v6, v6, v14
	v_mul_f32_e32 v7, v7, v15
	v_cvt_pk_bf16_f32 v0, v0, v1
	v_cvt_pk_bf16_f32 v1, v2, v3
	v_cvt_pk_bf16_f32 v2, v4, v5
	v_cvt_pk_bf16_f32 v3, v6, v7
	global_store_dwordx4 v24, v[0:3], s[2:3]
	s_mov_b64 exec, s[20:21]
	s_mov_b64 exec, s[12:13]
	v_mul_f32_e32 v16, v16, v28
	v_mul_f32_e32 v17, v17, v29
	v_mul_f32_e32 v18, v18, v30
	v_mul_f32_e32 v19, v19, v31
	v_mul_f32_e32 v20, v20, v32
	v_mul_f32_e32 v21, v21, v33
	v_mul_f32_e32 v22, v22, v34
	v_mul_f32_e32 v23, v23, v35
	v_cvt_pk_bf16_f32 v16, v16, v17
	v_cvt_pk_bf16_f32 v17, v18, v19
	v_cvt_pk_bf16_f32 v18, v20, v21
	v_cvt_pk_bf16_f32 v19, v22, v23
	global_store_dwordx4 v25, v[16:19], s[2:3]
	s_mov_b64 exec, s[20:21]
	v_cmp_gt_u32_e32 vcc, 0x3000, v27
	v_lshlrev_b32_e32 v38, 4, v27
	v_add_u32_e32 v38, 0xad0000, v38
	v_mov_b32_e32 v0, 0
	v_mov_b32_e32 v1, 0
	v_mov_b32_e32 v2, 0
	v_mov_b32_e32 v3, 0
	s_and_b64 exec, s[20:21], vcc
	global_store_dwordx4 v38, v[0:3], s[2:3]
	s_mov_b64 exec, s[20:21]
	.p2align 6
	s_nop 0
	s_nop 0
	s_nop 0
	s_nop 0
	s_nop 0
	s_nop 0
